# GEMM k-loop: first 4 MFMAs of every phase issued before the hand-off barrier
# speedup vs baseline: 1.0018x; 1.0018x over previous
; #define PG8_STAGE(bufoff, gbase, voff) do { _Pragma("unroll") for (int _i = 0; _i < 2; ++_i) \
;         __builtin_amdgcn_global_load_lds((const unsigned*)((const char*)(gbase) + (voff)[_i]), (LAS unsigned*)(lds + (bufoff) + ldsw + _i * 8192), 16, 0, 0); } while (0)
; #define PG8_LDA(dst, b, h) do { _Pragma("unroll") for (int m = 0; m < 4; ++m) _Pragma("unroll") for (int k = 0; k < 2; ++k) dst[m][k] = *(const LAS bf16x8*)(lds + PG8_SA(b, h) + aoff + m * 2048 + k * 1024); } while (0)
; #define PG8_LDB(dst, b, h) do { _Pragma("unroll") for (int n = 0; n < 2; ++n) _Pragma("unroll") for (int k = 0; k < 2; ++k) dst[n][k] = *(const LAS bf16x8*)(lds + PG8_SB(b, h) + boff + n * 2048 + k * 1024); } while (0)
; #define PG8_MMA(ai, bj, At, Bt) do { __builtin_amdgcn_s_setprio(1); _Pragma("unroll") for (int m = 0; m < 4; ++m) _Pragma("unroll") for (int n = 0; n < 2; ++n) _Pragma("unroll") for (int k = 0; k < 2; ++k) \
;         acc[ai][bj][m][n] = __builtin_amdgcn_mfma_f32_16x16x32_bf16(Bt[n][k], At[m][k], acc[ai][bj][m][n], 0, 0, 0); __builtin_amdgcn_s_setprio(0); } while (0)
; #define PG8_WAIT_V(n) asm volatile("s_waitcnt vmcnt(" #n ")" ::: "memory")
; #define PG8_WAIT_L(n) asm volatile("s_waitcnt lgkmcnt(" #n ")" ::: "memory")
; #define PG8_BAR __builtin_amdgcn_s_barrier()
; #define PG8_SCHED __builtin_amdgcn_sched_barrier(0)
; template <class Epi>
; __device__ __forceinline__ void gemm_phase(LAS unsigned char* lds, const Gemm g, const StaticOrder& S, const Epi& E) {
;     ...
;         for (int t = 0; t < nt; t += 2) {
;             const bool last = (t == nt - 2);
;             const char* a1 = cA + (size_t)(t + 1) * kstep;
;             const char* a2 = last ? nA : cA + (size_t)(t + 2) * kstep; const char* b2 = last ? nB : cB + (size_t)(t + 2) * kstep;
;             const char* a3 = a2 + kstep; const char* b3 = b2 + kstep;
;             PG8_LDB(B0, 0, 0); PG8_LDB(B1, 0, 1); PG8_SCHED; PG8_LDA(At, 0, 0); PG8_STAGE(PG8_SA(1, 1), a1 + hstep, voffA);
;             PG8_WAIT_V(8); PG8_WAIT_L(0); PG8_BAR; PG8_MMA(0, 0, At, B0); PG8_MMA(0, 1, At, B1); PG8_BAR; PG8_SCHED;
;             PG8_LDA(At, 0, 1); PG8_STAGE(PG8_SB(0, 0), b2, voffB); PG8_STAGE(PG8_SB(0, 1), b2 + hstep, voffB); PG8_STAGE(PG8_SA(0, 0), a2, voffA);
;             PG8_WAIT_V(8); PG8_WAIT_L(0); PG8_BAR; PG8_MMA(1, 0, At, B0); PG8_MMA(1, 1, At, B1); PG8_BAR; PG8_SCHED;
.LBB0_221:
	s_add_u32 s0, s6, 0x80
	s_addc_u32 s1, s7, 0
	s_add_u32 s6, s4, 0x100
	s_addc_u32 s7, s5, 0
	s_mov_b32 s4, 0
	s_waitcnt vmcnt(0)
	s_add_i32 s71, s4, 2
	s_add_u32 s72, s0, 0x80
	s_addc_u32 s5, s1, 0
	s_add_i32 s74, 0, 0x10000
	s_cmp_eq_u32 s62, s4
	s_cselect_b32 s5, s49, s5
	s_cselect_b32 s4, s48, s72
	s_cselect_b32 s73, s51, s7
	s_cselect_b32 s72, s50, s6
	s_add_i32 s75, 0, 0x14000
	v_add_u32_e32 v140, s74, v245
	v_add_u32_e32 v156, s75, v245
	ds_read_b128 v[128:131], v140
	ds_read_b128 v[132:135], v140 offset:1024
	ds_read_b128 v[136:139], v140 offset:2048
	ds_read_b128 v[140:143], v140 offset:3072
	ds_read_b128 v[144:147], v156
	ds_read_b128 v[148:151], v156 offset:1024
	ds_read_b128 v[152:155], v156 offset:2048
	ds_read_b128 v[156:159], v156 offset:3072
	v_lshl_add_u64 v[212:213], s[0:1], 0, v[208:209]
	s_add_i32 m0, s55, 0xc000
	ds_read_b128 v[160:163], v247
	ds_read_b128 v[164:167], v247 offset:1024
	ds_read_b128 v[168:171], v247 offset:2048
	ds_read_b128 v[172:175], v247 offset:3072
	ds_read_b128 v[176:179], v247 offset:4096
	ds_read_b128 v[180:183], v247 offset:5120
	ds_read_b128 v[184:187], v247 offset:6144
	ds_read_b128 v[188:191], v247 offset:7168
	global_load_lds_dwordx4 v[212:213], off
	v_lshl_add_u64 v[212:213], s[0:1], 0, v[210:211]
	s_add_i32 m0, s55, 0xe000
	s_nop 0
	global_load_lds_dwordx4 v[212:213], off
	s_waitcnt vmcnt(8)
	s_waitcnt lgkmcnt(0)
	v_mfma_f32_16x16x32_bf16 v[124:127], v[128:131], v[160:163], 0
	v_mfma_f32_16x16x32_bf16 v[120:123], v[136:139], v[160:163], 0
	v_mfma_f32_16x16x32_bf16 v[108:111], v[128:131], v[168:171], 0
	v_mfma_f32_16x16x32_bf16 v[104:107], v[136:139], v[168:171], 0
	s_barrier
	s_setprio 1
	s_waitcnt lgkmcnt(0)
	v_mfma_f32_16x16x32_bf16 v[92:95], v[128:131], v[176:179], 0
	v_mfma_f32_16x16x32_bf16 v[88:91], v[136:139], v[176:179], 0
	v_mfma_f32_16x16x32_bf16 v[76:79], v[128:131], v[184:187], 0
	v_mfma_f32_16x16x32_bf16 v[72:75], v[136:139], v[184:187], 0
	v_mfma_f32_16x16x32_bf16 v[124:127], v[132:135], v[164:167], v[124:127]
	v_mfma_f32_16x16x32_bf16 v[120:123], v[140:143], v[164:167], v[120:123]
	v_mfma_f32_16x16x32_bf16 v[108:111], v[132:135], v[172:175], v[108:111]
	v_mfma_f32_16x16x32_bf16 v[104:107], v[140:143], v[172:175], v[104:107]
	v_mfma_f32_16x16x32_bf16 v[92:95], v[132:135], v[180:183], v[92:95]
	v_mfma_f32_16x16x32_bf16 v[88:91], v[140:143], v[180:183], v[88:91]
	v_mfma_f32_16x16x32_bf16 v[76:79], v[132:135], v[188:191], v[76:79]
	v_mfma_f32_16x16x32_bf16 v[72:75], v[140:143], v[188:191], v[72:75]
	s_setprio 0
	s_setprio 1
	v_mfma_f32_16x16x32_bf16 v[116:119], v[144:147], v[160:163], 0
	v_mfma_f32_16x16x32_bf16 v[112:115], v[152:155], v[160:163], 0
	v_mfma_f32_16x16x32_bf16 v[100:103], v[144:147], v[168:171], 0
	v_mfma_f32_16x16x32_bf16 v[96:99], v[152:155], v[168:171], 0
	v_mfma_f32_16x16x32_bf16 v[84:87], v[144:147], v[176:179], 0
	v_mfma_f32_16x16x32_bf16 v[80:83], v[152:155], v[176:179], 0
	v_mfma_f32_16x16x32_bf16 v[68:71], v[144:147], v[184:187], 0
	v_mfma_f32_16x16x32_bf16 v[64:67], v[152:155], v[184:187], 0
	v_mfma_f32_16x16x32_bf16 v[116:119], v[148:151], v[164:167], v[116:119]
	v_mfma_f32_16x16x32_bf16 v[112:115], v[156:159], v[164:167], v[112:115]
	v_mfma_f32_16x16x32_bf16 v[100:103], v[148:151], v[172:175], v[100:103]
	v_mfma_f32_16x16x32_bf16 v[96:99], v[156:159], v[172:175], v[96:99]
	v_mfma_f32_16x16x32_bf16 v[84:87], v[148:151], v[180:183], v[84:87]
	v_mfma_f32_16x16x32_bf16 v[80:83], v[156:159], v[180:183], v[80:83]
	v_mfma_f32_16x16x32_bf16 v[68:71], v[148:151], v[188:191], v[68:71]
	v_mfma_f32_16x16x32_bf16 v[64:67], v[156:159], v[188:191], v[64:67]
	s_setprio 0
	s_barrier
	s_add_i32 s74, s74, s54
	v_lshl_add_u64 v[212:213], s[72:73], 0, v[192:193]
	s_mov_b32 m0, s74
	ds_read_b128 v[160:163], v247 offset:16384
	ds_read_b128 v[164:167], v247 offset:17408
	ds_read_b128 v[168:171], v247 offset:18432
	ds_read_b128 v[172:175], v247 offset:19456
	ds_read_b128 v[176:179], v247 offset:20480
	ds_read_b128 v[180:183], v247 offset:21504
	ds_read_b128 v[184:187], v247 offset:22528
	ds_read_b128 v[188:191], v247 offset:23552
	global_load_lds_dwordx4 v[212:213], off
	s_add_i32 m0, s74, 0x2000
	v_lshl_add_u64 v[214:215], s[72:73], 0, v[204:205]
	s_add_u32 s72, s72, s2
	s_addc_u32 s73, s73, 0
	s_add_i32 s74, s75, s54
	global_load_lds_dwordx4 v[214:215], off
	v_lshl_add_u64 v[216:217], s[72:73], 0, v[192:193]
	s_mov_b32 m0, s74
	v_lshl_add_u64 v[218:219], s[72:73], 0, v[204:205]
	global_load_lds_dwordx4 v[216:217], off
	s_add_i32 m0, s74, 0x2000
	v_lshl_add_u64 v[220:221], s[4:5], 0, v[200:201]
	global_load_lds_dwordx4 v[218:219], off
	s_mov_b32 m0, s55
	v_lshl_add_u64 v[222:223], s[4:5], 0, v[202:203]
	global_load_lds_dwordx4 v[220:221], off
	s_mov_b32 m0, s56
	s_nop 0
	global_load_lds_dwordx4 v[222:223], off
	s_waitcnt vmcnt(8)
	s_waitcnt lgkmcnt(0)
	v_mfma_f32_16x16x32_bf16 v[60:63], v[128:131], v[160:163], 0
	v_mfma_f32_16x16x32_bf16 v[56:59], v[136:139], v[160:163], 0
	v_mfma_f32_16x16x32_bf16 v[44:47], v[128:131], v[168:171], 0
	v_mfma_f32_16x16x32_bf16 v[40:43], v[136:139], v[168:171], 0
	s_barrier
; #define PG8_STAGE(bufoff, gbase, voff) do { _Pragma("unroll") for (int _i = 0; _i < 2; ++_i) \
;         __builtin_amdgcn_global_load_lds((const unsigned*)((const char*)(gbase) + (voff)[_i]), (LAS unsigned*)(lds + (bufoff) + ldsw + _i * 8192), 16, 0, 0); } while (0)
; #define PG8_LDA(dst, b, h) do { _Pragma("unroll") for (int m = 0; m < 4; ++m) _Pragma("unroll") for (int k = 0; k < 2; ++k) dst[m][k] = *(const LAS bf16x8*)(lds + PG8_SA(b, h) + aoff + m * 2048 + k * 1024); } while (0)
; #define PG8_LDB(dst, b, h) do { _Pragma("unroll") for (int n = 0; n < 2; ++n) _Pragma("unroll") for (int k = 0; k < 2; ++k) dst[n][k] = *(const LAS bf16x8*)(lds + PG8_SB(b, h) + boff + n * 2048 + k * 1024); } while (0)
; #define PG8_MMA(ai, bj, At, Bt) do { __builtin_amdgcn_s_setprio(1); _Pragma("unroll") for (int m = 0; m < 4; ++m) _Pragma("unroll") for (int n = 0; n < 2; ++n) _Pragma("unroll") for (int k = 0; k < 2; ++k) \
;         acc[ai][bj][m][n] = __builtin_amdgcn_mfma_f32_16x16x32_bf16(Bt[n][k], At[m][k], acc[ai][bj][m][n], 0, 0, 0); __builtin_amdgcn_s_setprio(0); } while (0)
; #define PG8_WAIT_V(n) asm volatile("s_waitcnt vmcnt(" #n ")" ::: "memory")
; #define PG8_WAIT_L(n) asm volatile("s_waitcnt lgkmcnt(" #n ")" ::: "memory")
; #define PG8_BAR __builtin_amdgcn_s_barrier()
; #define PG8_SCHED __builtin_amdgcn_sched_barrier(0)
; template <class Epi>
; __device__ __forceinline__ void gemm_phase(LAS unsigned char* lds, const Gemm g, const StaticOrder& S, const Epi& E) {
;     ...
;             PG8_LDA(At, 0, 1); PG8_STAGE(PG8_SB(0, 0), b2, voffB); PG8_STAGE(PG8_SB(0, 1), b2 + hstep, voffB); PG8_STAGE(PG8_SA(0, 0), a2, voffA);
;             PG8_WAIT_V(8); PG8_WAIT_L(0); PG8_BAR; PG8_MMA(1, 0, At, B0); PG8_MMA(1, 1, At, B1); PG8_BAR; PG8_SCHED;
;             PG8_LDB(B0, 1, 0); PG8_LDB(B1, 1, 1); PG8_SCHED; PG8_LDA(At, 1, 0); PG8_STAGE(PG8_SA(0, 1), a2 + hstep, voffA);
;             PG8_WAIT_V(8); PG8_WAIT_L(0); PG8_BAR; PG8_MMA(0, 0, At, B0); PG8_MMA(0, 1, At, B1); PG8_BAR; PG8_SCHED;
;             PG8_LDA(At, 1, 1); PG8_STAGE(PG8_SB(1, 0), b3, voffB); PG8_STAGE(PG8_SB(1, 1), b3 + hstep, voffB); PG8_STAGE(PG8_SA(1, 0), a3, voffA);
	s_setprio 1
	s_waitcnt lgkmcnt(0)
	v_mfma_f32_16x16x32_bf16 v[28:31], v[128:131], v[176:179], 0
	v_mfma_f32_16x16x32_bf16 v[24:27], v[136:139], v[176:179], 0
	v_mfma_f32_16x16x32_bf16 v[12:15], v[128:131], v[184:187], 0
	v_mfma_f32_16x16x32_bf16 v[8:11], v[136:139], v[184:187], 0
	v_mfma_f32_16x16x32_bf16 v[60:63], v[132:135], v[164:167], v[60:63]
	v_mfma_f32_16x16x32_bf16 v[56:59], v[140:143], v[164:167], v[56:59]
	v_mfma_f32_16x16x32_bf16 v[44:47], v[132:135], v[172:175], v[44:47]
	v_mfma_f32_16x16x32_bf16 v[40:43], v[140:143], v[172:175], v[40:43]
	v_mfma_f32_16x16x32_bf16 v[28:31], v[132:135], v[180:183], v[28:31]
	v_mfma_f32_16x16x32_bf16 v[24:27], v[140:143], v[180:183], v[24:27]
	v_mfma_f32_16x16x32_bf16 v[12:15], v[132:135], v[188:191], v[12:15]
	v_mfma_f32_16x16x32_bf16 v[8:11], v[140:143], v[188:191], v[8:11]
	s_setprio 0
	s_setprio 1
	v_mfma_f32_16x16x32_bf16 v[52:55], v[144:147], v[160:163], 0
	v_mfma_f32_16x16x32_bf16 v[48:51], v[152:155], v[160:163], 0
	v_mfma_f32_16x16x32_bf16 v[36:39], v[144:147], v[168:171], 0
	v_mfma_f32_16x16x32_bf16 v[32:35], v[152:155], v[168:171], 0
	v_mfma_f32_16x16x32_bf16 v[20:23], v[144:147], v[176:179], 0
	v_mfma_f32_16x16x32_bf16 v[16:19], v[152:155], v[176:179], 0
	v_mfma_f32_16x16x32_bf16 v[4:7], v[144:147], v[184:187], 0
	v_mfma_f32_16x16x32_bf16 v[0:3], v[152:155], v[184:187], 0
	v_mfma_f32_16x16x32_bf16 v[52:55], v[148:151], v[164:167], v[52:55]
	v_mfma_f32_16x16x32_bf16 v[48:51], v[156:159], v[164:167], v[48:51]
	v_mfma_f32_16x16x32_bf16 v[36:39], v[148:151], v[172:175], v[36:39]
	v_mfma_f32_16x16x32_bf16 v[32:35], v[156:159], v[172:175], v[32:35]
	v_mfma_f32_16x16x32_bf16 v[20:23], v[148:151], v[180:183], v[20:23]
	v_mfma_f32_16x16x32_bf16 v[16:19], v[156:159], v[180:183], v[16:19]
	v_mfma_f32_16x16x32_bf16 v[4:7], v[148:151], v[188:191], v[4:7]
	v_mfma_f32_16x16x32_bf16 v[0:3], v[156:159], v[188:191], v[0:3]
	s_setprio 0
	s_barrier
	s_add_i32 s72, 0, 0x18000
	s_add_i32 s73, 0, 0x1c000
	v_add_u32_e32 v140, s72, v245
	v_add_u32_e32 v156, s73, v245
	ds_read_b128 v[128:131], v140
	ds_read_b128 v[132:135], v140 offset:1024
	ds_read_b128 v[136:139], v140 offset:2048
	ds_read_b128 v[140:143], v140 offset:3072
	ds_read_b128 v[144:147], v156
	ds_read_b128 v[148:151], v156 offset:1024
	ds_read_b128 v[152:155], v156 offset:2048
	ds_read_b128 v[156:159], v156 offset:3072
	s_add_u32 s4, s4, s2
	s_addc_u32 s5, s5, 0
	s_mov_b32 m0, s57
	v_lshl_add_u64 v[224:225], s[4:5], 0, v[200:201]
	ds_read_b128 v[160:163], v247 offset:32768
	ds_read_b128 v[164:167], v247 offset:33792
	ds_read_b128 v[168:171], v247 offset:34816
	ds_read_b128 v[172:175], v247 offset:35840
	ds_read_b128 v[176:179], v247 offset:36864
	ds_read_b128 v[180:183], v247 offset:37888
	ds_read_b128 v[184:187], v247 offset:38912
	ds_read_b128 v[188:191], v247 offset:39936
	global_load_lds_dwordx4 v[224:225], off
	v_lshl_add_u64 v[224:225], s[4:5], 0, v[202:203]
	s_mov_b32 m0, s58
	s_nop 0
	global_load_lds_dwordx4 v[224:225], off
	s_waitcnt vmcnt(8)
	s_waitcnt lgkmcnt(0)
	v_mfma_f32_16x16x32_bf16 v[124:127], v[128:131], v[160:163], v[124:127]
	v_mfma_f32_16x16x32_bf16 v[120:123], v[136:139], v[160:163], v[120:123]
	v_mfma_f32_16x16x32_bf16 v[108:111], v[128:131], v[168:171], v[108:111]
	v_mfma_f32_16x16x32_bf16 v[104:107], v[136:139], v[168:171], v[104:107]
	s_barrier
	s_setprio 1
	s_waitcnt lgkmcnt(0)
	v_mfma_f32_16x16x32_bf16 v[92:95], v[128:131], v[176:179], v[92:95]
	v_mfma_f32_16x16x32_bf16 v[88:91], v[136:139], v[176:179], v[88:91]
	v_mfma_f32_16x16x32_bf16 v[76:79], v[128:131], v[184:187], v[76:79]
	v_mfma_f32_16x16x32_bf16 v[72:75], v[136:139], v[184:187], v[72:75]
	v_mfma_f32_16x16x32_bf16 v[124:127], v[132:135], v[164:167], v[124:127]
	v_mfma_f32_16x16x32_bf16 v[120:123], v[140:143], v[164:167], v[120:123]
	v_mfma_f32_16x16x32_bf16 v[108:111], v[132:135], v[172:175], v[108:111]
	v_mfma_f32_16x16x32_bf16 v[104:107], v[140:143], v[172:175], v[104:107]
	v_mfma_f32_16x16x32_bf16 v[92:95], v[132:135], v[180:183], v[92:95]
	v_mfma_f32_16x16x32_bf16 v[88:91], v[140:143], v[180:183], v[88:91]
	v_mfma_f32_16x16x32_bf16 v[76:79], v[132:135], v[188:191], v[76:79]
	v_mfma_f32_16x16x32_bf16 v[72:75], v[140:143], v[188:191], v[72:75]
	s_setprio 0
	s_setprio 1
	v_mfma_f32_16x16x32_bf16 v[116:119], v[144:147], v[160:163], v[116:119]
	v_mfma_f32_16x16x32_bf16 v[112:115], v[152:155], v[160:163], v[112:115]
	v_mfma_f32_16x16x32_bf16 v[100:103], v[144:147], v[168:171], v[100:103]
	v_mfma_f32_16x16x32_bf16 v[96:99], v[152:155], v[168:171], v[96:99]
	v_mfma_f32_16x16x32_bf16 v[84:87], v[144:147], v[176:179], v[84:87]
	v_mfma_f32_16x16x32_bf16 v[80:83], v[152:155], v[176:179], v[80:83]
	v_mfma_f32_16x16x32_bf16 v[68:71], v[144:147], v[184:187], v[68:71]
	v_mfma_f32_16x16x32_bf16 v[64:67], v[152:155], v[184:187], v[64:67]
	v_mfma_f32_16x16x32_bf16 v[116:119], v[148:151], v[164:167], v[116:119]
	v_mfma_f32_16x16x32_bf16 v[112:115], v[156:159], v[164:167], v[112:115]
	v_mfma_f32_16x16x32_bf16 v[100:103], v[148:151], v[172:175], v[100:103]
	v_mfma_f32_16x16x32_bf16 v[96:99], v[156:159], v[172:175], v[96:99]
	v_mfma_f32_16x16x32_bf16 v[84:87], v[148:151], v[180:183], v[84:87]
	v_mfma_f32_16x16x32_bf16 v[80:83], v[156:159], v[180:183], v[80:83]
	v_mfma_f32_16x16x32_bf16 v[68:71], v[148:151], v[188:191], v[68:71]
	v_mfma_f32_16x16x32_bf16 v[64:67], v[156:159], v[188:191], v[64:67]
	s_setprio 0
	s_barrier
; #define PG8_STAGE(bufoff, gbase, voff) do { _Pragma("unroll") for (int _i = 0; _i < 2; ++_i) \
;         __builtin_amdgcn_global_load_lds((const unsigned*)((const char*)(gbase) + (voff)[_i]), (LAS unsigned*)(lds + (bufoff) + ldsw + _i * 8192), 16, 0, 0); } while (0)
; #define PG8_LDA(dst, b, h) do { _Pragma("unroll") for (int m = 0; m < 4; ++m) _Pragma("unroll") for (int k = 0; k < 2; ++k) dst[m][k] = *(const LAS bf16x8*)(lds + PG8_SA(b, h) + aoff + m * 2048 + k * 1024); } while (0)
; #define PG8_LDB(dst, b, h) do { _Pragma("unroll") for (int n = 0; n < 2; ++n) _Pragma("unroll") for (int k = 0; k < 2; ++k) dst[n][k] = *(const LAS bf16x8*)(lds + PG8_SB(b, h) + boff + n * 2048 + k * 1024); } while (0)
; #define PG8_MMA(ai, bj, At, Bt) do { __builtin_amdgcn_s_setprio(1); _Pragma("unroll") for (int m = 0; m < 4; ++m) _Pragma("unroll") for (int n = 0; n < 2; ++n) _Pragma("unroll") for (int k = 0; k < 2; ++k) \
;         acc[ai][bj][m][n] = __builtin_amdgcn_mfma_f32_16x16x32_bf16(Bt[n][k], At[m][k], acc[ai][bj][m][n], 0, 0, 0); __builtin_amdgcn_s_setprio(0); } while (0)
; #define PG8_WAIT_V(n) asm volatile("s_waitcnt vmcnt(" #n ")" ::: "memory")
; #define PG8_WAIT_L(n) asm volatile("s_waitcnt lgkmcnt(" #n ")" ::: "memory")
; #define PG8_BAR __builtin_amdgcn_s_barrier()
; #define PG8_SCHED __builtin_amdgcn_sched_barrier(0)
; template <class Epi>
; __device__ __forceinline__ void gemm_phase(LAS unsigned char* lds, const Gemm g, const StaticOrder& S, const Epi& E) {
;     ...
;         for (int t = 0; t < nt; t += 2) {
;             const bool last = (t == nt - 2);
;             const char* a1 = cA + (size_t)(t + 1) * kstep;
;             const char* a2 = last ? nA : cA + (size_t)(t + 2) * kstep; const char* b2 = last ? nB : cB + (size_t)(t + 2) * kstep;
;             const char* a3 = a2 + kstep; const char* b3 = b2 + kstep;
;             PG8_LDB(B0, 0, 0); PG8_LDB(B1, 0, 1); PG8_SCHED; PG8_LDA(At, 0, 0); PG8_STAGE(PG8_SA(1, 1), a1 + hstep, voffA);
;             PG8_WAIT_V(8); PG8_WAIT_L(0); PG8_BAR; PG8_MMA(0, 0, At, B0); PG8_MMA(0, 1, At, B1); PG8_BAR; PG8_SCHED;
;     ...
;             PG8_LDA(At, 1, 1); PG8_STAGE(PG8_SB(1, 0), b3, voffB); PG8_STAGE(PG8_SB(1, 1), b3 + hstep, voffB); PG8_STAGE(PG8_SA(1, 0), a3, voffA);
;             PG8_WAIT_V(8); PG8_WAIT_L(0); PG8_BAR; PG8_MMA(1, 0, At, B0); PG8_MMA(1, 1, At, B1); PG8_BAR; PG8_SCHED;
	s_add_i32 s4, s72, s54
	v_lshl_add_u64 v[212:213], v[212:213], 0, s[12:13]
	s_mov_b32 m0, s4
	ds_read_b128 v[160:163], v247 offset:49152
	ds_read_b128 v[164:167], v247 offset:50176
	ds_read_b128 v[168:171], v247 offset:51200
	ds_read_b128 v[172:175], v247 offset:52224
	ds_read_b128 v[176:179], v247 offset:53248
	ds_read_b128 v[180:183], v247 offset:54272
	ds_read_b128 v[184:187], v247 offset:55296
	ds_read_b128 v[188:191], v247 offset:56320
	global_load_lds_dwordx4 v[212:213], off
	v_lshl_add_u64 v[212:213], v[214:215], 0, s[12:13]
	s_add_i32 m0, s4, 0x2000
	s_add_i32 s4, s73, s54
	global_load_lds_dwordx4 v[212:213], off
	v_lshl_add_u64 v[212:213], v[216:217], 0, s[12:13]
	s_mov_b32 m0, s4
	s_nop 0
	global_load_lds_dwordx4 v[212:213], off
	v_lshl_add_u64 v[212:213], v[218:219], 0, s[12:13]
	s_add_i32 m0, s4, 0x2000
	s_nop 0
	global_load_lds_dwordx4 v[212:213], off
	v_lshl_add_u64 v[212:213], v[220:221], 0, s[12:13]
	s_mov_b32 m0, s59
	s_nop 0
	global_load_lds_dwordx4 v[212:213], off
	v_lshl_add_u64 v[212:213], v[222:223], 0, s[12:13]
	s_mov_b32 m0, s60
	s_nop 0
	global_load_lds_dwordx4 v[212:213], off
	s_waitcnt vmcnt(8)
	s_waitcnt lgkmcnt(0)
	v_mfma_f32_16x16x32_bf16 v[60:63], v[128:131], v[160:163], v[60:63]
	v_mfma_f32_16x16x32_bf16 v[56:59], v[136:139], v[160:163], v[56:59]
	v_mfma_f32_16x16x32_bf16 v[44:47], v[128:131], v[168:171], v[44:47]
	v_mfma_f32_16x16x32_bf16 v[40:43], v[136:139], v[168:171], v[40:43]
	s_barrier
	s_setprio 1
	s_waitcnt lgkmcnt(0)
	v_mfma_f32_16x16x32_bf16 v[28:31], v[128:131], v[176:179], v[28:31]
	v_mfma_f32_16x16x32_bf16 v[24:27], v[136:139], v[176:179], v[24:27]
	v_mfma_f32_16x16x32_bf16 v[12:15], v[128:131], v[184:187], v[12:15]
	v_mfma_f32_16x16x32_bf16 v[8:11], v[136:139], v[184:187], v[8:11]
	v_mfma_f32_16x16x32_bf16 v[60:63], v[132:135], v[164:167], v[60:63]
	v_mfma_f32_16x16x32_bf16 v[56:59], v[140:143], v[164:167], v[56:59]
	v_mfma_f32_16x16x32_bf16 v[44:47], v[132:135], v[172:175], v[44:47]
	v_mfma_f32_16x16x32_bf16 v[40:43], v[140:143], v[172:175], v[40:43]
	v_mfma_f32_16x16x32_bf16 v[28:31], v[132:135], v[180:183], v[28:31]
	v_mfma_f32_16x16x32_bf16 v[24:27], v[140:143], v[180:183], v[24:27]
	v_mfma_f32_16x16x32_bf16 v[12:15], v[132:135], v[188:191], v[12:15]
	v_mfma_f32_16x16x32_bf16 v[8:11], v[140:143], v[188:191], v[8:11]
	s_setprio 0
	s_setprio 1
	v_mfma_f32_16x16x32_bf16 v[52:55], v[144:147], v[160:163], v[52:55]
	v_mfma_f32_16x16x32_bf16 v[48:51], v[152:155], v[160:163], v[48:51]
	v_mfma_f32_16x16x32_bf16 v[36:39], v[144:147], v[168:171], v[36:39]
	v_mfma_f32_16x16x32_bf16 v[32:35], v[152:155], v[168:171], v[32:35]
	v_mfma_f32_16x16x32_bf16 v[20:23], v[144:147], v[176:179], v[20:23]
	v_mfma_f32_16x16x32_bf16 v[16:19], v[152:155], v[176:179], v[16:19]
	v_mfma_f32_16x16x32_bf16 v[4:7], v[144:147], v[184:187], v[4:7]
	v_mfma_f32_16x16x32_bf16 v[0:3], v[152:155], v[184:187], v[0:3]
	v_mfma_f32_16x16x32_bf16 v[52:55], v[148:151], v[164:167], v[52:55]
	v_mfma_f32_16x16x32_bf16 v[48:51], v[156:159], v[164:167], v[48:51]
	v_mfma_f32_16x16x32_bf16 v[36:39], v[148:151], v[172:175], v[36:39]
	v_mfma_f32_16x16x32_bf16 v[32:35], v[156:159], v[172:175], v[32:35]
	v_mfma_f32_16x16x32_bf16 v[20:23], v[148:151], v[180:183], v[20:23]
	v_mfma_f32_16x16x32_bf16 v[16:19], v[156:159], v[180:183], v[16:19]
	v_mfma_f32_16x16x32_bf16 v[4:7], v[148:151], v[188:191], v[4:7]
	v_mfma_f32_16x16x32_bf16 v[0:3], v[156:159], v[188:191], v[0:3]
	s_setprio 0
	s_barrier
	s_add_u32 s0, s0, 0x100
	s_addc_u32 s1, s1, 0
	s_add_u32 s6, s6, 0x100
	s_addc_u32 s7, s7, 0
	s_cmp_ge_u32 s71, s61
	s_mov_b32 s4, s71
	s_cbranch_scc1 .Lk_done
.LBB0_222:
	s_add_i32 s71, s4, 2
	s_add_u32 s72, s0, 0x80
	s_addc_u32 s5, s1, 0
	s_add_i32 s74, 0, 0x10000
	s_cmp_eq_u32 s62, s4
	s_cselect_b32 s5, s49, s5
	s_cselect_b32 s4, s48, s72
	s_cselect_b32 s73, s51, s7
	s_cselect_b32 s72, s50, s6
	s_add_i32 s75, 0, 0x14000
	v_add_u32_e32 v140, s74, v245
	v_add_u32_e32 v156, s75, v245
	ds_read_b128 v[128:131], v140
	ds_read_b128 v[132:135], v140 offset:1024
	ds_read_b128 v[136:139], v140 offset:2048
	ds_read_b128 v[140:143], v140 offset:3072
	ds_read_b128 v[144:147], v156
	ds_read_b128 v[148:151], v156 offset:1024
	ds_read_b128 v[152:155], v156 offset:2048
	ds_read_b128 v[156:159], v156 offset:3072
	v_lshl_add_u64 v[212:213], s[0:1], 0, v[208:209]
	s_add_i32 m0, s55, 0xc000
	ds_read_b128 v[160:163], v247
	ds_read_b128 v[164:167], v247 offset:1024
	ds_read_b128 v[168:171], v247 offset:2048
	ds_read_b128 v[172:175], v247 offset:3072
	ds_read_b128 v[176:179], v247 offset:4096
	ds_read_b128 v[180:183], v247 offset:5120
	ds_read_b128 v[184:187], v247 offset:6144
	ds_read_b128 v[188:191], v247 offset:7168
	global_load_lds_dwordx4 v[212:213], off
	v_lshl_add_u64 v[212:213], s[0:1], 0, v[210:211]
	s_add_i32 m0, s55, 0xe000
	s_nop 0
	global_load_lds_dwordx4 v[212:213], off
	s_waitcnt vmcnt(8)
	s_waitcnt lgkmcnt(0)
	v_mfma_f32_16x16x32_bf16 v[124:127], v[128:131], v[160:163], v[124:127]
	v_mfma_f32_16x16x32_bf16 v[120:123], v[136:139], v[160:163], v[120:123]
	v_mfma_f32_16x16x32_bf16 v[108:111], v[128:131], v[168:171], v[108:111]
	v_mfma_f32_16x16x32_bf16 v[104:107], v[136:139], v[168:171], v[104:107]
	s_barrier
; #define PG8_STAGE(bufoff, gbase, voff) do { _Pragma("unroll") for (int _i = 0; _i < 2; ++_i) \
;         __builtin_amdgcn_global_load_lds((const unsigned*)((const char*)(gbase) + (voff)[_i]), (LAS unsigned*)(lds + (bufoff) + ldsw + _i * 8192), 16, 0, 0); } while (0)
; #define PG8_LDA(dst, b, h) do { _Pragma("unroll") for (int m = 0; m < 4; ++m) _Pragma("unroll") for (int k = 0; k < 2; ++k) dst[m][k] = *(const LAS bf16x8*)(lds + PG8_SA(b, h) + aoff + m * 2048 + k * 1024); } while (0)
; #define PG8_MMA(ai, bj, At, Bt) do { __builtin_amdgcn_s_setprio(1); _Pragma("unroll") for (int m = 0; m < 4; ++m) _Pragma("unroll") for (int n = 0; n < 2; ++n) _Pragma("unroll") for (int k = 0; k < 2; ++k) \
;         acc[ai][bj][m][n] = __builtin_amdgcn_mfma_f32_16x16x32_bf16(Bt[n][k], At[m][k], acc[ai][bj][m][n], 0, 0, 0); __builtin_amdgcn_s_setprio(0); } while (0)
; #define PG8_WAIT_V(n) asm volatile("s_waitcnt vmcnt(" #n ")" ::: "memory")
; #define PG8_WAIT_L(n) asm volatile("s_waitcnt lgkmcnt(" #n ")" ::: "memory")
; #define PG8_BAR __builtin_amdgcn_s_barrier()
; #define PG8_SCHED __builtin_amdgcn_sched_barrier(0)
; template <class Epi>
; __device__ __forceinline__ void gemm_phase(LAS unsigned char* lds, const Gemm g, const StaticOrder& S, const Epi& E) {
;     ...
;             PG8_WAIT_V(8); PG8_WAIT_L(0); PG8_BAR; PG8_MMA(0, 0, At, B0); PG8_MMA(0, 1, At, B1); PG8_BAR; PG8_SCHED;
;             PG8_LDA(At, 0, 1); PG8_STAGE(PG8_SB(0, 0), b2, voffB); PG8_STAGE(PG8_SB(0, 1), b2 + hstep, voffB); PG8_STAGE(PG8_SA(0, 0), a2, voffA);
;             PG8_WAIT_V(8); PG8_WAIT_L(0); PG8_BAR; PG8_MMA(1, 0, At, B0); PG8_MMA(1, 1, At, B1); PG8_BAR; PG8_SCHED;
	s_setprio 1
	s_waitcnt lgkmcnt(0)
	v_mfma_f32_16x16x32_bf16 v[92:95], v[128:131], v[176:179], v[92:95]
	v_mfma_f32_16x16x32_bf16 v[88:91], v[136:139], v[176:179], v[88:91]
	v_mfma_f32_16x16x32_bf16 v[76:79], v[128:131], v[184:187], v[76:79]
	v_mfma_f32_16x16x32_bf16 v[72:75], v[136:139], v[184:187], v[72:75]
	v_mfma_f32_16x16x32_bf16 v[124:127], v[132:135], v[164:167], v[124:127]
	v_mfma_f32_16x16x32_bf16 v[120:123], v[140:143], v[164:167], v[120:123]
	v_mfma_f32_16x16x32_bf16 v[108:111], v[132:135], v[172:175], v[108:111]
	v_mfma_f32_16x16x32_bf16 v[104:107], v[140:143], v[172:175], v[104:107]
	v_mfma_f32_16x16x32_bf16 v[92:95], v[132:135], v[180:183], v[92:95]
	v_mfma_f32_16x16x32_bf16 v[88:91], v[140:143], v[180:183], v[88:91]
	v_mfma_f32_16x16x32_bf16 v[76:79], v[132:135], v[188:191], v[76:79]
	v_mfma_f32_16x16x32_bf16 v[72:75], v[140:143], v[188:191], v[72:75]
	s_setprio 0
	s_setprio 1
	v_mfma_f32_16x16x32_bf16 v[116:119], v[144:147], v[160:163], v[116:119]
	v_mfma_f32_16x16x32_bf16 v[112:115], v[152:155], v[160:163], v[112:115]
	v_mfma_f32_16x16x32_bf16 v[100:103], v[144:147], v[168:171], v[100:103]
	v_mfma_f32_16x16x32_bf16 v[96:99], v[152:155], v[168:171], v[96:99]
	v_mfma_f32_16x16x32_bf16 v[84:87], v[144:147], v[176:179], v[84:87]
	v_mfma_f32_16x16x32_bf16 v[80:83], v[152:155], v[176:179], v[80:83]
	v_mfma_f32_16x16x32_bf16 v[68:71], v[144:147], v[184:187], v[68:71]
	v_mfma_f32_16x16x32_bf16 v[64:67], v[152:155], v[184:187], v[64:67]
	v_mfma_f32_16x16x32_bf16 v[116:119], v[148:151], v[164:167], v[116:119]
	v_mfma_f32_16x16x32_bf16 v[112:115], v[156:159], v[164:167], v[112:115]
	v_mfma_f32_16x16x32_bf16 v[100:103], v[148:151], v[172:175], v[100:103]
	v_mfma_f32_16x16x32_bf16 v[96:99], v[156:159], v[172:175], v[96:99]
	v_mfma_f32_16x16x32_bf16 v[84:87], v[148:151], v[180:183], v[84:87]
	v_mfma_f32_16x16x32_bf16 v[80:83], v[156:159], v[180:183], v[80:83]
	v_mfma_f32_16x16x32_bf16 v[68:71], v[148:151], v[188:191], v[68:71]
	v_mfma_f32_16x16x32_bf16 v[64:67], v[156:159], v[188:191], v[64:67]
	s_setprio 0
	s_barrier
	s_add_i32 s74, s74, s54
	v_lshl_add_u64 v[212:213], s[72:73], 0, v[192:193]
	s_mov_b32 m0, s74
	ds_read_b128 v[160:163], v247 offset:16384
	ds_read_b128 v[164:167], v247 offset:17408
	ds_read_b128 v[168:171], v247 offset:18432
	ds_read_b128 v[172:175], v247 offset:19456
	ds_read_b128 v[176:179], v247 offset:20480
	ds_read_b128 v[180:183], v247 offset:21504
	ds_read_b128 v[184:187], v247 offset:22528
	ds_read_b128 v[188:191], v247 offset:23552
	global_load_lds_dwordx4 v[212:213], off
	s_add_i32 m0, s74, 0x2000
	v_lshl_add_u64 v[214:215], s[72:73], 0, v[204:205]
	s_add_u32 s72, s72, s2
	s_addc_u32 s73, s73, 0
	s_add_i32 s74, s75, s54
	global_load_lds_dwordx4 v[214:215], off
	v_lshl_add_u64 v[216:217], s[72:73], 0, v[192:193]
	s_mov_b32 m0, s74
	v_lshl_add_u64 v[218:219], s[72:73], 0, v[204:205]
	global_load_lds_dwordx4 v[216:217], off
	s_add_i32 m0, s74, 0x2000
	v_lshl_add_u64 v[220:221], s[4:5], 0, v[200:201]
	global_load_lds_dwordx4 v[218:219], off
	s_mov_b32 m0, s55
	v_lshl_add_u64 v[222:223], s[4:5], 0, v[202:203]
	global_load_lds_dwordx4 v[220:221], off
	s_mov_b32 m0, s56
	s_nop 0
	global_load_lds_dwordx4 v[222:223], off
	s_waitcnt vmcnt(8)
	s_waitcnt lgkmcnt(0)
	v_mfma_f32_16x16x32_bf16 v[60:63], v[128:131], v[160:163], v[60:63]
	v_mfma_f32_16x16x32_bf16 v[56:59], v[136:139], v[160:163], v[56:59]
	v_mfma_f32_16x16x32_bf16 v[44:47], v[128:131], v[168:171], v[44:47]
	v_mfma_f32_16x16x32_bf16 v[40:43], v[136:139], v[168:171], v[40:43]
	s_barrier
	s_setprio 1
	s_waitcnt lgkmcnt(0)
	v_mfma_f32_16x16x32_bf16 v[28:31], v[128:131], v[176:179], v[28:31]
	v_mfma_f32_16x16x32_bf16 v[24:27], v[136:139], v[176:179], v[24:27]
	v_mfma_f32_16x16x32_bf16 v[12:15], v[128:131], v[184:187], v[12:15]
	v_mfma_f32_16x16x32_bf16 v[8:11], v[136:139], v[184:187], v[8:11]
	v_mfma_f32_16x16x32_bf16 v[60:63], v[132:135], v[164:167], v[60:63]
	v_mfma_f32_16x16x32_bf16 v[56:59], v[140:143], v[164:167], v[56:59]
	v_mfma_f32_16x16x32_bf16 v[44:47], v[132:135], v[172:175], v[44:47]
	v_mfma_f32_16x16x32_bf16 v[40:43], v[140:143], v[172:175], v[40:43]
	v_mfma_f32_16x16x32_bf16 v[28:31], v[132:135], v[180:183], v[28:31]
	v_mfma_f32_16x16x32_bf16 v[24:27], v[140:143], v[180:183], v[24:27]
	v_mfma_f32_16x16x32_bf16 v[12:15], v[132:135], v[188:191], v[12:15]
	v_mfma_f32_16x16x32_bf16 v[8:11], v[140:143], v[188:191], v[8:11]
	s_setprio 0
	s_setprio 1
	v_mfma_f32_16x16x32_bf16 v[52:55], v[144:147], v[160:163], v[52:55]
	v_mfma_f32_16x16x32_bf16 v[48:51], v[152:155], v[160:163], v[48:51]
	v_mfma_f32_16x16x32_bf16 v[36:39], v[144:147], v[168:171], v[36:39]
	v_mfma_f32_16x16x32_bf16 v[32:35], v[152:155], v[168:171], v[32:35]
	v_mfma_f32_16x16x32_bf16 v[20:23], v[144:147], v[176:179], v[20:23]
	v_mfma_f32_16x16x32_bf16 v[16:19], v[152:155], v[176:179], v[16:19]
	v_mfma_f32_16x16x32_bf16 v[4:7], v[144:147], v[184:187], v[4:7]
	v_mfma_f32_16x16x32_bf16 v[0:3], v[152:155], v[184:187], v[0:3]
	v_mfma_f32_16x16x32_bf16 v[52:55], v[148:151], v[164:167], v[52:55]
	v_mfma_f32_16x16x32_bf16 v[48:51], v[156:159], v[164:167], v[48:51]
	v_mfma_f32_16x16x32_bf16 v[36:39], v[148:151], v[172:175], v[36:39]
	v_mfma_f32_16x16x32_bf16 v[32:35], v[156:159], v[172:175], v[32:35]
	v_mfma_f32_16x16x32_bf16 v[20:23], v[148:151], v[180:183], v[20:23]
	v_mfma_f32_16x16x32_bf16 v[16:19], v[156:159], v[180:183], v[16:19]
	v_mfma_f32_16x16x32_bf16 v[4:7], v[148:151], v[188:191], v[4:7]
	v_mfma_f32_16x16x32_bf16 v[0:3], v[156:159], v[188:191], v[0:3]
	s_setprio 0
	s_barrier
; #define PG8_STAGE(bufoff, gbase, voff) do { _Pragma("unroll") for (int _i = 0; _i < 2; ++_i) \
;         __builtin_amdgcn_global_load_lds((const unsigned*)((const char*)(gbase) + (voff)[_i]), (LAS unsigned*)(lds + (bufoff) + ldsw + _i * 8192), 16, 0, 0); } while (0)
; #define PG8_LDA(dst, b, h) do { _Pragma("unroll") for (int m = 0; m < 4; ++m) _Pragma("unroll") for (int k = 0; k < 2; ++k) dst[m][k] = *(const LAS bf16x8*)(lds + PG8_SA(b, h) + aoff + m * 2048 + k * 1024); } while (0)
; #define PG8_LDB(dst, b, h) do { _Pragma("unroll") for (int n = 0; n < 2; ++n) _Pragma("unroll") for (int k = 0; k < 2; ++k) dst[n][k] = *(const LAS bf16x8*)(lds + PG8_SB(b, h) + boff + n * 2048 + k * 1024); } while (0)
; #define PG8_MMA(ai, bj, At, Bt) do { __builtin_amdgcn_s_setprio(1); _Pragma("unroll") for (int m = 0; m < 4; ++m) _Pragma("unroll") for (int n = 0; n < 2; ++n) _Pragma("unroll") for (int k = 0; k < 2; ++k) \
;         acc[ai][bj][m][n] = __builtin_amdgcn_mfma_f32_16x16x32_bf16(Bt[n][k], At[m][k], acc[ai][bj][m][n], 0, 0, 0); __builtin_amdgcn_s_setprio(0); } while (0)
; #define PG8_WAIT_V(n) asm volatile("s_waitcnt vmcnt(" #n ")" ::: "memory")
; #define PG8_WAIT_L(n) asm volatile("s_waitcnt lgkmcnt(" #n ")" ::: "memory")
; #define PG8_BAR __builtin_amdgcn_s_barrier()
; #define PG8_SCHED __builtin_amdgcn_sched_barrier(0)
; template <class Epi>
; __device__ __forceinline__ void gemm_phase(LAS unsigned char* lds, const Gemm g, const StaticOrder& S, const Epi& E) {
;     ...
;             PG8_LDB(B0, 1, 0); PG8_LDB(B1, 1, 1); PG8_SCHED; PG8_LDA(At, 1, 0); PG8_STAGE(PG8_SA(0, 1), a2 + hstep, voffA);
;             PG8_WAIT_V(8); PG8_WAIT_L(0); PG8_BAR; PG8_MMA(0, 0, At, B0); PG8_MMA(0, 1, At, B1); PG8_BAR; PG8_SCHED;
	s_add_i32 s72, 0, 0x18000
	s_add_i32 s73, 0, 0x1c000
	v_add_u32_e32 v140, s72, v245
	v_add_u32_e32 v156, s73, v245
	ds_read_b128 v[128:131], v140
	ds_read_b128 v[132:135], v140 offset:1024
	ds_read_b128 v[136:139], v140 offset:2048
	ds_read_b128 v[140:143], v140 offset:3072
	ds_read_b128 v[144:147], v156
	ds_read_b128 v[148:151], v156 offset:1024
	ds_read_b128 v[152:155], v156 offset:2048
	ds_read_b128 v[156:159], v156 offset:3072
	s_add_u32 s4, s4, s2
	s_addc_u32 s5, s5, 0
	s_mov_b32 m0, s57
	v_lshl_add_u64 v[224:225], s[4:5], 0, v[200:201]
	ds_read_b128 v[160:163], v247 offset:32768
	ds_read_b128 v[164:167], v247 offset:33792
	ds_read_b128 v[168:171], v247 offset:34816
	ds_read_b128 v[172:175], v247 offset:35840
	ds_read_b128 v[176:179], v247 offset:36864
	ds_read_b128 v[180:183], v247 offset:37888
	ds_read_b128 v[184:187], v247 offset:38912
	ds_read_b128 v[188:191], v247 offset:39936
	global_load_lds_dwordx4 v[224:225], off
	v_lshl_add_u64 v[224:225], s[4:5], 0, v[202:203]
	s_mov_b32 m0, s58
	s_nop 0
	global_load_lds_dwordx4 v[224:225], off
	s_waitcnt vmcnt(8)
	s_waitcnt lgkmcnt(0)
	v_mfma_f32_16x16x32_bf16 v[124:127], v[128:131], v[160:163], v[124:127]
	v_mfma_f32_16x16x32_bf16 v[120:123], v[136:139], v[160:163], v[120:123]
	v_mfma_f32_16x16x32_bf16 v[108:111], v[128:131], v[168:171], v[108:111]
	v_mfma_f32_16x16x32_bf16 v[104:107], v[136:139], v[168:171], v[104:107]
	s_barrier
	s_setprio 1
	s_waitcnt lgkmcnt(0)
	v_mfma_f32_16x16x32_bf16 v[92:95], v[128:131], v[176:179], v[92:95]
	v_mfma_f32_16x16x32_bf16 v[88:91], v[136:139], v[176:179], v[88:91]
	v_mfma_f32_16x16x32_bf16 v[76:79], v[128:131], v[184:187], v[76:79]
	v_mfma_f32_16x16x32_bf16 v[72:75], v[136:139], v[184:187], v[72:75]
	v_mfma_f32_16x16x32_bf16 v[124:127], v[132:135], v[164:167], v[124:127]
	v_mfma_f32_16x16x32_bf16 v[120:123], v[140:143], v[164:167], v[120:123]
	v_mfma_f32_16x16x32_bf16 v[108:111], v[132:135], v[172:175], v[108:111]
	v_mfma_f32_16x16x32_bf16 v[104:107], v[140:143], v[172:175], v[104:107]
	v_mfma_f32_16x16x32_bf16 v[92:95], v[132:135], v[180:183], v[92:95]
	v_mfma_f32_16x16x32_bf16 v[88:91], v[140:143], v[180:183], v[88:91]
	v_mfma_f32_16x16x32_bf16 v[76:79], v[132:135], v[188:191], v[76:79]
	v_mfma_f32_16x16x32_bf16 v[72:75], v[140:143], v[188:191], v[72:75]
	s_setprio 0
	s_setprio 1
	v_mfma_f32_16x16x32_bf16 v[116:119], v[144:147], v[160:163], v[116:119]
	v_mfma_f32_16x16x32_bf16 v[112:115], v[152:155], v[160:163], v[112:115]
	v_mfma_f32_16x16x32_bf16 v[100:103], v[144:147], v[168:171], v[100:103]
	v_mfma_f32_16x16x32_bf16 v[96:99], v[152:155], v[168:171], v[96:99]
	v_mfma_f32_16x16x32_bf16 v[84:87], v[144:147], v[176:179], v[84:87]
	v_mfma_f32_16x16x32_bf16 v[80:83], v[152:155], v[176:179], v[80:83]
	v_mfma_f32_16x16x32_bf16 v[68:71], v[144:147], v[184:187], v[68:71]
	v_mfma_f32_16x16x32_bf16 v[64:67], v[152:155], v[184:187], v[64:67]
	v_mfma_f32_16x16x32_bf16 v[116:119], v[148:151], v[164:167], v[116:119]
	v_mfma_f32_16x16x32_bf16 v[112:115], v[156:159], v[164:167], v[112:115]
	v_mfma_f32_16x16x32_bf16 v[100:103], v[148:151], v[172:175], v[100:103]
	v_mfma_f32_16x16x32_bf16 v[96:99], v[156:159], v[172:175], v[96:99]
	v_mfma_f32_16x16x32_bf16 v[84:87], v[148:151], v[180:183], v[84:87]
	v_mfma_f32_16x16x32_bf16 v[80:83], v[156:159], v[180:183], v[80:83]
	v_mfma_f32_16x16x32_bf16 v[68:71], v[148:151], v[188:191], v[68:71]
	v_mfma_f32_16x16x32_bf16 v[64:67], v[156:159], v[188:191], v[64:67]
	s_setprio 0
	s_barrier
; #define PG8_STAGE(bufoff, gbase, voff) do { _Pragma("unroll") for (int _i = 0; _i < 2; ++_i) \
;         __builtin_amdgcn_global_load_lds((const unsigned*)((const char*)(gbase) + (voff)[_i]), (LAS unsigned*)(lds + (bufoff) + ldsw + _i * 8192), 16, 0, 0); } while (0)
; #define PG8_LDA(dst, b, h) do { _Pragma("unroll") for (int m = 0; m < 4; ++m) _Pragma("unroll") for (int k = 0; k < 2; ++k) dst[m][k] = *(const LAS bf16x8*)(lds + PG8_SA(b, h) + aoff + m * 2048 + k * 1024); } while (0)
; #define PG8_MMA(ai, bj, At, Bt) do { __builtin_amdgcn_s_setprio(1); _Pragma("unroll") for (int m = 0; m < 4; ++m) _Pragma("unroll") for (int n = 0; n < 2; ++n) _Pragma("unroll") for (int k = 0; k < 2; ++k) \
;         acc[ai][bj][m][n] = __builtin_amdgcn_mfma_f32_16x16x32_bf16(Bt[n][k], At[m][k], acc[ai][bj][m][n], 0, 0, 0); __builtin_amdgcn_s_setprio(0); } while (0)
; #define PG8_WAIT_V(n) asm volatile("s_waitcnt vmcnt(" #n ")" ::: "memory")
; #define PG8_WAIT_L(n) asm volatile("s_waitcnt lgkmcnt(" #n ")" ::: "memory")
; #define PG8_BAR __builtin_amdgcn_s_barrier()
; #define PG8_SCHED __builtin_amdgcn_sched_barrier(0)
; template <class Epi>
; __device__ __forceinline__ void gemm_phase(LAS unsigned char* lds, const Gemm g, const StaticOrder& S, const Epi& E) {
;     ...
;             PG8_LDA(At, 1, 1); PG8_STAGE(PG8_SB(1, 0), b3, voffB); PG8_STAGE(PG8_SB(1, 1), b3 + hstep, voffB); PG8_STAGE(PG8_SA(1, 0), a3, voffA);
;             PG8_WAIT_V(8); PG8_WAIT_L(0); PG8_BAR; PG8_MMA(1, 0, At, B0); PG8_MMA(1, 1, At, B1); PG8_BAR; PG8_SCHED;
;         }
	s_add_i32 s4, s72, s54
	v_lshl_add_u64 v[212:213], v[212:213], 0, s[12:13]
	s_mov_b32 m0, s4
	ds_read_b128 v[160:163], v247 offset:49152
	ds_read_b128 v[164:167], v247 offset:50176
	ds_read_b128 v[168:171], v247 offset:51200
	ds_read_b128 v[172:175], v247 offset:52224
	ds_read_b128 v[176:179], v247 offset:53248
	ds_read_b128 v[180:183], v247 offset:54272
	ds_read_b128 v[184:187], v247 offset:55296
	ds_read_b128 v[188:191], v247 offset:56320
	global_load_lds_dwordx4 v[212:213], off
	v_lshl_add_u64 v[212:213], v[214:215], 0, s[12:13]
	s_add_i32 m0, s4, 0x2000
	s_add_i32 s4, s73, s54
	global_load_lds_dwordx4 v[212:213], off
	v_lshl_add_u64 v[212:213], v[216:217], 0, s[12:13]
	s_mov_b32 m0, s4
	s_nop 0
	global_load_lds_dwordx4 v[212:213], off
	v_lshl_add_u64 v[212:213], v[218:219], 0, s[12:13]
	s_add_i32 m0, s4, 0x2000
	s_nop 0
	global_load_lds_dwordx4 v[212:213], off
	v_lshl_add_u64 v[212:213], v[220:221], 0, s[12:13]
	s_mov_b32 m0, s59
	s_nop 0
	global_load_lds_dwordx4 v[212:213], off
	v_lshl_add_u64 v[212:213], v[222:223], 0, s[12:13]
	s_mov_b32 m0, s60
	s_nop 0
	global_load_lds_dwordx4 v[212:213], off
	s_waitcnt vmcnt(8)
	s_waitcnt lgkmcnt(0)
	v_mfma_f32_16x16x32_bf16 v[60:63], v[128:131], v[160:163], v[60:63]
	v_mfma_f32_16x16x32_bf16 v[56:59], v[136:139], v[160:163], v[56:59]
	v_mfma_f32_16x16x32_bf16 v[44:47], v[128:131], v[168:171], v[44:47]
	v_mfma_f32_16x16x32_bf16 v[40:43], v[136:139], v[168:171], v[40:43]
	s_barrier
	s_setprio 1
	s_waitcnt lgkmcnt(0)
	v_mfma_f32_16x16x32_bf16 v[28:31], v[128:131], v[176:179], v[28:31]
	v_mfma_f32_16x16x32_bf16 v[24:27], v[136:139], v[176:179], v[24:27]
	v_mfma_f32_16x16x32_bf16 v[12:15], v[128:131], v[184:187], v[12:15]
	v_mfma_f32_16x16x32_bf16 v[8:11], v[136:139], v[184:187], v[8:11]
	v_mfma_f32_16x16x32_bf16 v[60:63], v[132:135], v[164:167], v[60:63]
	v_mfma_f32_16x16x32_bf16 v[56:59], v[140:143], v[164:167], v[56:59]
	v_mfma_f32_16x16x32_bf16 v[44:47], v[132:135], v[172:175], v[44:47]
	v_mfma_f32_16x16x32_bf16 v[40:43], v[140:143], v[172:175], v[40:43]
	v_mfma_f32_16x16x32_bf16 v[28:31], v[132:135], v[180:183], v[28:31]
	v_mfma_f32_16x16x32_bf16 v[24:27], v[140:143], v[180:183], v[24:27]
	v_mfma_f32_16x16x32_bf16 v[12:15], v[132:135], v[188:191], v[12:15]
	v_mfma_f32_16x16x32_bf16 v[8:11], v[140:143], v[188:191], v[8:11]
	s_setprio 0
	s_setprio 1
	v_mfma_f32_16x16x32_bf16 v[52:55], v[144:147], v[160:163], v[52:55]
	v_mfma_f32_16x16x32_bf16 v[48:51], v[152:155], v[160:163], v[48:51]
	v_mfma_f32_16x16x32_bf16 v[36:39], v[144:147], v[168:171], v[36:39]
	v_mfma_f32_16x16x32_bf16 v[32:35], v[152:155], v[168:171], v[32:35]
	v_mfma_f32_16x16x32_bf16 v[20:23], v[144:147], v[176:179], v[20:23]
	v_mfma_f32_16x16x32_bf16 v[16:19], v[152:155], v[176:179], v[16:19]
	v_mfma_f32_16x16x32_bf16 v[4:7], v[144:147], v[184:187], v[4:7]
	v_mfma_f32_16x16x32_bf16 v[0:3], v[152:155], v[184:187], v[0:3]
	v_mfma_f32_16x16x32_bf16 v[52:55], v[148:151], v[164:167], v[52:55]
	v_mfma_f32_16x16x32_bf16 v[48:51], v[156:159], v[164:167], v[48:51]
	v_mfma_f32_16x16x32_bf16 v[36:39], v[148:151], v[172:175], v[36:39]
	v_mfma_f32_16x16x32_bf16 v[32:35], v[156:159], v[172:175], v[32:35]
	v_mfma_f32_16x16x32_bf16 v[20:23], v[148:151], v[180:183], v[20:23]
	v_mfma_f32_16x16x32_bf16 v[16:19], v[156:159], v[180:183], v[16:19]
	v_mfma_f32_16x16x32_bf16 v[4:7], v[148:151], v[188:191], v[4:7]
	v_mfma_f32_16x16x32_bf16 v[0:3], v[156:159], v[188:191], v[0:3]
	s_setprio 0
	s_barrier
	s_add_u32 s0, s0, 0x100
	s_addc_u32 s1, s1, 0
	s_add_u32 s6, s6, 0x100
	s_addc_u32 s7, s7, 0
	s_cmp_ge_u32 s71, s61
	s_mov_b32 s4, s71
	s_cbranch_scc0 .LBB0_222
